# scan loop: packed f32 muls beside MFMAs split into scalar muls; static priority raise for the computing waves over the staging waves
# speedup vs baseline: 1.0070x; 1.0070x over previous
; DI void scan_phase(LAS unsigned char* lds, const Args& a, int l) {
;     ...
;         float* dp = a.out + OUT_DP + (size_t)((l * 8 + b) * 4 + h) * 16384 + (size_t)(4 * fq) * 128 + 16 * s + fr;
; #pragma unroll
;         for (int mt = 0; mt < 8; ++mt)
; #pragma unroll
;             for (int reg = 0; reg < 4; ++reg) __builtin_nontemporal_store(S[mt][reg], dp + (size_t)(16 * mt + reg) * 128);
;     }
.LBB0_106:
	s_setprio 0
	s_and_b32 s2, s8, -4
	s_add_i32 s2, s2, s14
	s_or_b32 s10, s2, s16
	s_ashr_i32 s11, s10, 31
	s_lshl_b64 s[10:11], s[10:11], 16
	s_movk_i32 s2, 0x6000
	s_add_i32 s8, s8, s24
	v_lshl_add_u64 v[32:33], v[134:135], 0, s[10:11]
	global_store_dword v[32:33], v0, off nt
	global_store_dword v[32:33], v1, off offset:512 nt
	global_store_dword v[32:33], v2, off offset:1024 nt
	global_store_dword v[32:33], v3, off offset:1536 nt
	v_add_co_u32_e32 v0, vcc, s93, v32
	s_nop 1
	v_addc_co_u32_e32 v1, vcc, 0, v33, vcc
	global_store_dword v[0:1], v4, off nt
	global_store_dword v[0:1], v5, off offset:512 nt
	global_store_dword v[0:1], v6, off offset:1024 nt
	global_store_dword v[0:1], v7, off offset:1536 nt
	v_add_co_u32_e32 v0, vcc, s45, v32
	s_nop 1
	v_addc_co_u32_e32 v1, vcc, 0, v33, vcc
	global_store_dword v[0:1], v8, off nt
	global_store_dword v[0:1], v9, off offset:512 nt
	global_store_dword v[0:1], v10, off offset:1024 nt
	global_store_dword v[0:1], v11, off offset:1536 nt
	v_add_co_u32_e32 v0, vcc, s2, v32
	s_mov_b32 s2, 0xa000
	s_nop 0
	v_addc_co_u32_e32 v1, vcc, 0, v33, vcc
	global_store_dword v[0:1], v12, off nt
	global_store_dword v[0:1], v13, off offset:512 nt
	global_store_dword v[0:1], v14, off offset:1024 nt
	global_store_dword v[0:1], v15, off offset:1536 nt
	v_add_co_u32_e32 v0, vcc, s49, v32
	s_nop 1
	v_addc_co_u32_e32 v1, vcc, 0, v33, vcc
	global_store_dword v[0:1], v16, off nt
	global_store_dword v[0:1], v17, off offset:512 nt
	global_store_dword v[0:1], v18, off offset:1024 nt
	global_store_dword v[0:1], v19, off offset:1536 nt
	v_add_co_u32_e32 v0, vcc, s2, v32
	s_mov_b32 s2, 0xc000
	s_nop 0
	v_addc_co_u32_e32 v1, vcc, 0, v33, vcc
	global_store_dword v[0:1], v20, off nt
	global_store_dword v[0:1], v21, off offset:512 nt
	global_store_dword v[0:1], v22, off offset:1024 nt
	global_store_dword v[0:1], v23, off offset:1536 nt
	v_add_co_u32_e32 v0, vcc, s2, v32
	v_readlane_b32 s2, v254, 51
	s_nop 0
	v_addc_co_u32_e32 v1, vcc, 0, v33, vcc
	global_store_dword v[0:1], v24, off nt
	global_store_dword v[0:1], v25, off offset:512 nt
	global_store_dword v[0:1], v26, off offset:1024 nt
	global_store_dword v[0:1], v27, off offset:1536 nt
	v_add_co_u32_e32 v0, vcc, 0xe000, v32
	s_add_i32 s15, s15, s2
	s_nop 0
	v_addc_co_u32_e32 v1, vcc, 0, v33, vcc
	s_cmp_gt_i32 s8, 31
	global_store_dword v[0:1], v28, off nt
	global_store_dword v[0:1], v29, off offset:512 nt
	global_store_dword v[0:1], v30, off offset:1024 nt
	global_store_dword v[0:1], v31, off offset:1536 nt
	s_cbranch_scc1 .LBB0_112

; #define LAS __attribute__((address_space(3)))
; #define MFMA16(a, b, c) __builtin_amdgcn_mfma_f32_16x16x32_bf16((a), (b), (c), 0, 0, 0)
; #define SC_LOADUV(it_) do { const float* _u = (const float*)(a.ws + WS_UV) + (size_t)(it_) * 8192 + s * 1024 + lane * 4; \
;         uvn[0] = *(const f32x4*)_u; uvn[1] = *(const f32x4*)(_u + 256); uvn[2] = *(const f32x4*)(_u + 512); uvn[3] = *(const f32x4*)(_u + 768); \
;         gen = ((const float*)(a.ws + WS_GE))[(it_)]; } while (0)
; #define SC_STORE(bo_) do { LAS unsigned char* _b = lds + (bo_); \
;         *(LAS u32x4*)(_b + O_WK + lw0) = pf[0]; *(LAS u32x4*)(_b + O_WK + lw1) = pf[1]; *(LAS u32x4*)(_b + O_QD + lw0) = pf[2]; *(LAS u32x4*)(_b + O_QD + lw1) = pf[3]; \
;         *(LAS u32x4*)(_b + O_KET + lk0) = pf[4]; *(LAS u32x4*)(_b + O_KET + lk1) = pf[5]; *(LAS u32x4*)(_b + O_QK + lk0) = pf[6]; } while (0)
; DI void scan_phase(LAS unsigned char* lds, const Args& a, int l) {
;     ...
;         for (int n = 0; n < 32; ++n) {
;             const int cur = (n & 1) * BUF;
;             if (n + 1 < 32) { SC_STORE(BUF - cur); SC_LOADUV(item0 + n + 1); }
;             if (n + 2 < 32) SC_LOADG(item0 + n + 2);
;             const LAS unsigned char* B = lds + cur;
;             f32x4 ws[4], o[4];
; #pragma unroll
;             for (int m = 0; m < 4; ++m) { ws[m] = (f32x4){0.f, 0.f, 0.f, 0.f}; o[m] = (f32x4){0.f, 0.f, 0.f, 0.f}; }
; #pragma unroll
;             for (int ks = 0; ks < 4; ++ks)
; #pragma unroll
;                 for (int m = 0; m < 4; ++m) { const bf16x8 av = *(const LAS bf16x8*)(B + O_WK + (16 * m + fr) * 272 + (32 * ks + 8 * fq) * 2); ws[m] = MFMA16(av, Sb[ks], ws[m]); }
.LBB0_108:
	s_cmp_lg_u32 s101, 0
	s_cbranch_scc1 .Lscan_idle
	s_setprio 2
	s_bitcmp1_b32 s9, 0
	s_cselect_b32 s2, 0xf400, 0
	v_add3_u32 v250, s2, v113, v115
	v_add3_u32 v251, s2, v113, v117
	ds_read_b128 v[214:217], v250
	ds_read_b128 v[218:221], v250 offset:4352
	ds_read_b128 v[222:225], v250 offset:8704
	ds_read_b128 v[226:229], v250 offset:13056
	ds_read_b128 v[230:233], v250 offset:64
	ds_read_b128 v[234:237], v250 offset:4416
	ds_read_b128 v[238:241], v250 offset:8768
	s_cmp_eq_u32 s9, 31
	s_cbranch_scc1 .Lscan_nostage
	s_sub_i32 s10, 0, s2
	v_add_u32_e32 v32, s10, v110
	s_add_i32 s11, s10, 0xf400
	ds_write_b128 v32, v[48:51] offset:62464
	v_add_u32_e32 v33, s10, v112
	ds_write_b128 v33, v[52:55] offset:62464
	v_add_u32_e32 v32, s11, v110
	ds_write_b128 v32, v[56:59] offset:17408
	v_add_u32_e32 v33, s11, v112
	ds_write_b128 v33, v[60:63] offset:17408
	v_add_u32_e32 v32, s11, v114
	v_add_u32_e32 v33, s11, v116
	ds_write_b128 v32, v[64:67] offset:34816
	ds_write_b128 v33, v[68:71] offset:34816
	v_add_u32_e32 v32, s11, v151
	ds_write_b128 v32, v[72:75] offset:53248

; #define LAS __attribute__((address_space(3)))
; DI bf16x8 pack8(const f32x4& a, const f32x4& b) { u32x4 p; p.x = pk2(a[0], a[1]); p.y = pk2(a[2], a[3]); p.z = pk2(b[0], b[1]); p.w = pk2(b[2], b[3]); return __builtin_bit_cast(bf16x8, p); }
; #define MFMA16(a, b, c) __builtin_amdgcn_mfma_f32_16x16x32_bf16((a), (b), (c), 0, 0, 0)
; DI void scan_phase(LAS unsigned char* lds, const Args& a, int l) {
;     ...
;             for (int ks = 0; ks < 4; ++ks)
; #pragma unroll
;                 for (int m = 0; m < 4; ++m) { const bf16x8 av = *(const LAS bf16x8*)(B + O_WK + (16 * m + fr) * 272 + (32 * ks + 8 * fq) * 2); ws[m] = MFMA16(av, Sb[ks], ws[m]); }
; #pragma unroll
;             for (int ks = 0; ks < 4; ++ks)
; #pragma unroll
;                 for (int m = 0; m < 4; ++m) { const bf16x8 av = *(const LAS bf16x8*)(B + O_QD + (16 * m + fr) * 272 + (32 * ks + 8 * fq) * 2); o[m] = MFMA16(av, Sb[ks], o[m]); }
;             f32x4 u[4];
; #pragma unroll
;             for (int m = 0; m < 4; ++m) u[m] = uvc[m] - ws[m];
;             bf16x8 Ub[2]; Ub[0] = pack8(u[0], u[1]); Ub[1] = pack8(u[2], u[3]);
; #pragma unroll
;             for (int ks = 0; ks < 2; ++ks)
; #pragma unroll
;                 for (int m = 0; m < 4; ++m) { const bf16x8 av = *(const LAS bf16x8*)(B + O_QK + (16 * m + fr) * 144 + (32 * ks + 8 * fq) * 2); o[m] = MFMA16(av, Ub[ks], o[m]); }
; #pragma unroll
;             for (int mt = 0; mt < 8; ++mt) S[mt] = S[mt] * gec;
.LBB0_110:
	ds_read_b128 v[242:245], v250 offset:13120
	s_waitcnt lgkmcnt(7)
	v_mfma_f32_16x16x32_bf16 v[182:185], v[214:217], v[88:91], 0
	v_mul_f32_e32 v0, v150, v0
	v_mul_f32_e32 v1, v150, v1
	ds_read_b128 v[214:217], v250 offset:128
	s_waitcnt lgkmcnt(7)
	v_mfma_f32_16x16x32_bf16 v[186:189], v[218:221], v[88:91], 0
	v_mul_f32_e32 v2, v150, v2
	v_mul_f32_e32 v3, v150, v3
	s_mov_b64 s[10:11], 0x4000
	v_lshl_add_u64 v[146:147], v[146:147], 0, s[10:11]
	ds_read_b128 v[218:221], v250 offset:4480
	s_waitcnt lgkmcnt(7)
	v_mfma_f32_16x16x32_bf16 v[190:193], v[222:225], v[88:91], 0
	v_mul_f32_e32 v4, v150, v4
	v_mul_f32_e32 v5, v150, v5
	ds_read_b128 v[222:225], v250 offset:8832
	s_waitcnt lgkmcnt(7)
	v_mfma_f32_16x16x32_bf16 v[194:197], v[226:229], v[88:91], 0
	v_mul_f32_e32 v6, v150, v6
	v_mul_f32_e32 v7, v150, v7
	s_add_u32 s17, s17, 4
	s_addc_u32 s28, s28, 0
	ds_read_b128 v[226:229], v250 offset:13184
	s_waitcnt lgkmcnt(7)
	v_mfma_f32_16x16x32_bf16 v[182:185], v[230:233], v[84:87], v[182:185]
	v_mul_f32_e32 v8, v150, v8
	v_mul_f32_e32 v9, v150, v9
	ds_read_b128 v[230:233], v250 offset:192
	s_waitcnt lgkmcnt(7)
	v_mfma_f32_16x16x32_bf16 v[186:189], v[234:237], v[84:87], v[186:189]
	v_mul_f32_e32 v10, v150, v10
	v_mul_f32_e32 v11, v150, v11
	v_lshl_add_u64 v[144:145], v[144:145], 0, s[26:27]
	ds_read_b128 v[234:237], v250 offset:4544
	s_waitcnt lgkmcnt(7)
	v_mfma_f32_16x16x32_bf16 v[190:193], v[238:241], v[84:87], v[190:193]
	v_mul_f32_e32 v12, v150, v12
	v_mul_f32_e32 v13, v150, v13
	ds_read_b128 v[238:241], v250 offset:8896
	s_waitcnt lgkmcnt(7)
	v_mfma_f32_16x16x32_bf16 v[194:197], v[242:245], v[84:87], v[194:197]
	v_mul_f32_e32 v14, v150, v14
	v_mul_f32_e32 v15, v150, v15
	s_mov_b64 s[10:11], 0x8000
	v_lshl_add_u64 v[148:149], v[148:149], 0, s[10:11]
	ds_read_b128 v[242:245], v250 offset:13248
	s_waitcnt lgkmcnt(7)
	v_mfma_f32_16x16x32_bf16 v[182:185], v[214:217], v[80:83], v[182:185]
	v_mul_f32_e32 v16, v150, v16
	v_mul_f32_e32 v17, v150, v17
	ds_read_b128 v[214:217], v250 offset:17408
	s_waitcnt lgkmcnt(7)
	v_mfma_f32_16x16x32_bf16 v[186:189], v[218:221], v[80:83], v[186:189]
	v_mul_f32_e32 v18, v150, v18
	v_mul_f32_e32 v19, v150, v19
	ds_read_b128 v[218:221], v250 offset:21760
	s_waitcnt lgkmcnt(7)
	v_mfma_f32_16x16x32_bf16 v[190:193], v[222:225], v[80:83], v[190:193]
	v_mul_f32_e32 v20, v150, v20
	v_mul_f32_e32 v21, v150, v21
	ds_read_b128 v[222:225], v250 offset:26112
	s_waitcnt lgkmcnt(7)
	v_mfma_f32_16x16x32_bf16 v[194:197], v[226:229], v[80:83], v[194:197]
	v_mul_f32_e32 v22, v150, v22
	v_mul_f32_e32 v23, v150, v23
	ds_read_b128 v[226:229], v250 offset:30464
	s_waitcnt lgkmcnt(7)
	v_mfma_f32_16x16x32_bf16 v[182:185], v[230:233], v[76:79], v[182:185]
	v_mul_f32_e32 v24, v150, v24
	v_mul_f32_e32 v25, v150, v25
	ds_read_b128 v[230:233], v250 offset:17472
	s_waitcnt lgkmcnt(7)
	v_mfma_f32_16x16x32_bf16 v[186:189], v[234:237], v[76:79], v[186:189]
	v_mul_f32_e32 v26, v150, v26
	v_mul_f32_e32 v27, v150, v27
	ds_read_b128 v[234:237], v250 offset:21824
	s_waitcnt lgkmcnt(7)
	v_mfma_f32_16x16x32_bf16 v[190:193], v[238:241], v[76:79], v[190:193]
	v_mul_f32_e32 v28, v150, v28
	v_mul_f32_e32 v29, v150, v29
	ds_read_b128 v[238:241], v250 offset:26176
	s_waitcnt lgkmcnt(7)
	v_mfma_f32_16x16x32_bf16 v[194:197], v[242:245], v[76:79], v[194:197]
	v_mul_f32_e32 v30, v150, v30
	v_mul_f32_e32 v31, v150, v31
	ds_read_b128 v[242:245], v250 offset:30528
	s_waitcnt lgkmcnt(7)
	v_mfma_f32_16x16x32_bf16 v[198:201], v[214:217], v[88:91], 0
	ds_read_b128 v[214:217], v250 offset:17536
	s_waitcnt lgkmcnt(7)
	v_mfma_f32_16x16x32_bf16 v[202:205], v[218:221], v[88:91], 0
	v_sub_f32_e32 v182, v104, v182
	v_sub_f32_e32 v183, v105, v183
	v_sub_f32_e32 v184, v106, v184
	v_sub_f32_e32 v185, v107, v185
	ds_read_b128 v[218:221], v250 offset:21888
	s_waitcnt lgkmcnt(7)
	v_mfma_f32_16x16x32_bf16 v[206:209], v[222:225], v[88:91], 0
	v_sub_f32_e32 v186, v96, v186
	v_sub_f32_e32 v187, v97, v187
	v_sub_f32_e32 v188, v98, v188
	v_sub_f32_e32 v189, v99, v189
	ds_read_b128 v[222:225], v250 offset:26240
	s_waitcnt lgkmcnt(7)
	v_mfma_f32_16x16x32_bf16 v[210:213], v[226:229], v[88:91], 0
	v_sub_f32_e32 v190, v92, v190
	v_sub_f32_e32 v191, v93, v191
	v_sub_f32_e32 v192, v94, v192
	v_sub_f32_e32 v193, v95, v193
	ds_read_b128 v[226:229], v250 offset:30592
	s_waitcnt lgkmcnt(7)
	v_mfma_f32_16x16x32_bf16 v[198:201], v[230:233], v[84:87], v[198:201]
	v_sub_f32_e32 v194, v100, v194
	v_sub_f32_e32 v195, v101, v195
	v_sub_f32_e32 v196, v102, v196
	v_sub_f32_e32 v197, v103, v197
	ds_read_b128 v[230:233], v250 offset:17600
	s_waitcnt lgkmcnt(7)
	v_mfma_f32_16x16x32_bf16 v[202:205], v[234:237], v[84:87], v[202:205]
	v_cvt_pk_bf16_f32 v246, v182, v183
	v_cvt_pk_bf16_f32 v247, v184, v185
	ds_read_b128 v[234:237], v250 offset:21952
	s_waitcnt lgkmcnt(7)
	v_mfma_f32_16x16x32_bf16 v[206:209], v[238:241], v[84:87], v[206:209]
	v_cvt_pk_bf16_f32 v248, v186, v187
	v_cvt_pk_bf16_f32 v249, v188, v189
	ds_read_b128 v[238:241], v250 offset:26304
	s_waitcnt lgkmcnt(7)
	v_mfma_f32_16x16x32_bf16 v[210:213], v[242:245], v[84:87], v[210:213]
	v_cvt_pk_bf16_f32 v182, v190, v191
	v_cvt_pk_bf16_f32 v183, v192, v193
	ds_read_b128 v[242:245], v250 offset:30656
	s_waitcnt lgkmcnt(7)
	v_mfma_f32_16x16x32_bf16 v[198:201], v[214:217], v[80:83], v[198:201]
	v_cvt_pk_bf16_f32 v184, v194, v195
	v_cvt_pk_bf16_f32 v185, v196, v197
	ds_read_b128 v[214:217], v251 offset:34816
	s_waitcnt lgkmcnt(7)
	v_mfma_f32_16x16x32_bf16 v[202:205], v[218:221], v[80:83], v[202:205]
	ds_read_b128 v[218:221], v251 offset:39424
	s_waitcnt lgkmcnt(7)
	v_mfma_f32_16x16x32_bf16 v[206:209], v[222:225], v[80:83], v[206:209]
	ds_read_b128 v[222:225], v251 offset:44032
	s_waitcnt lgkmcnt(7)
; #define LAS __attribute__((address_space(3)))
; DI bf16x8 pack8(const f32x4& a, const f32x4& b) { u32x4 p; p.x = pk2(a[0], a[1]); p.y = pk2(a[2], a[3]); p.z = pk2(b[0], b[1]); p.w = pk2(b[2], b[3]); return __builtin_bit_cast(bf16x8, p); }
; #define MFMA16(a, b, c) __builtin_amdgcn_mfma_f32_16x16x32_bf16((a), (b), (c), 0, 0, 0)
; DI void scan_phase(LAS unsigned char* lds, const Args& a, int l) {
;     ...
;                 for (int m = 0; m < 4; ++m) { const bf16x8 av = *(const LAS bf16x8*)(B + O_QK + (16 * m + fr) * 144 + (32 * ks + 8 * fq) * 2); o[m] = MFMA16(av, Ub[ks], o[m]); }
; #pragma unroll
;             for (int mt = 0; mt < 8; ++mt) S[mt] = S[mt] * gec;
; #pragma unroll
;             for (int ks = 0; ks < 2; ++ks)
; #pragma unroll
;                 for (int mt = 0; mt < 8; ++mt) { const bf16x8 av = *(const LAS bf16x8*)(B + O_KET + (16 * mt + fr) * 144 + (32 * ks + 8 * fq) * 2); S[mt] = MFMA16(av, Ub[ks], S[mt]); }
; #pragma unroll
;             for (int ks = 0; ks < 4; ++ks) Sb[ks] = pack8(S[2 * ks], S[2 * ks + 1]);
;             float* op = O + (size_t)(b * 2048 + n * 64 + 4 * fq) * 512 + h * 128 + 16 * s + fr;
; #pragma unroll
;             for (int m = 0; m < 4; ++m)
; #pragma unroll
;                 for (int reg = 0; reg < 4; ++reg) op[(size_t)(16 * m + reg) * 512] = o[m][reg];
; #pragma unroll
;             for (int m = 0; m < 4; ++m) uvc[m] = uvn[m];
;             gec = gen;
;             __syncthreads();
;         }
	v_mfma_f32_16x16x32_bf16 v[210:213], v[226:229], v[80:83], v[210:213]
	ds_read_b128 v[226:229], v251 offset:48640
	s_waitcnt lgkmcnt(7)
	v_mfma_f32_16x16x32_bf16 v[198:201], v[230:233], v[76:79], v[198:201]
	ds_read_b128 v[230:233], v251 offset:34960
	s_waitcnt lgkmcnt(7)
	v_mfma_f32_16x16x32_bf16 v[202:205], v[234:237], v[76:79], v[202:205]
	ds_read_b128 v[234:237], v251 offset:39568
	s_waitcnt lgkmcnt(7)
	v_mfma_f32_16x16x32_bf16 v[206:209], v[238:241], v[76:79], v[206:209]
	ds_read_b128 v[238:241], v251 offset:44176
	s_waitcnt lgkmcnt(7)
	v_mfma_f32_16x16x32_bf16 v[210:213], v[242:245], v[76:79], v[210:213]
	ds_read_b128 v[242:245], v251 offset:48784
	s_waitcnt lgkmcnt(7)
	v_mfma_f32_16x16x32_bf16 v[0:3], v[214:217], v[246:249], v[0:3]
	ds_read_b128 v[214:217], v251 offset:34880
	s_waitcnt lgkmcnt(7)
	v_mfma_f32_16x16x32_bf16 v[4:7], v[218:221], v[246:249], v[4:7]
	ds_read_b128 v[218:221], v251 offset:39488
	s_waitcnt lgkmcnt(7)
	v_mfma_f32_16x16x32_bf16 v[8:11], v[222:225], v[246:249], v[8:11]
	v_ashrrev_i32_e32 v143, 31, v142
	ds_read_b128 v[222:225], v251 offset:44096
	s_waitcnt lgkmcnt(7)
	v_mfma_f32_16x16x32_bf16 v[12:15], v[226:229], v[246:249], v[12:15]
	ds_read_b128 v[226:229], v251 offset:48704
	s_waitcnt lgkmcnt(7)
	v_mfma_f32_16x16x32_bf16 v[16:19], v[230:233], v[246:249], v[16:19]
	v_lshlrev_b64 v[162:163], 11, v[142:143]
	ds_read_b128 v[230:233], v251 offset:35024
	s_waitcnt lgkmcnt(7)
	v_mfma_f32_16x16x32_bf16 v[20:23], v[234:237], v[246:249], v[20:23]
	ds_read_b128 v[234:237], v251 offset:39632
	s_waitcnt lgkmcnt(7)
	v_mfma_f32_16x16x32_bf16 v[24:27], v[238:241], v[246:249], v[24:27]
	v_lshl_add_u64 v[162:163], v[140:141], 0, v[162:163]
	ds_read_b128 v[238:241], v251 offset:44240
	s_waitcnt lgkmcnt(7)
	v_mfma_f32_16x16x32_bf16 v[28:31], v[242:245], v[246:249], v[28:31]
	ds_read_b128 v[242:245], v251 offset:48848
	s_waitcnt lgkmcnt(7)
	v_mfma_f32_16x16x32_bf16 v[0:3], v[214:217], v[182:185], v[0:3]
	v_add_u32_e32 v142, 64, v142
	ds_read_b128 v[214:217], v251 offset:53248
	s_waitcnt lgkmcnt(7)
	v_mfma_f32_16x16x32_bf16 v[4:7], v[218:221], v[182:185], v[4:7]
	ds_read_b128 v[218:221], v251 offset:57856
	s_waitcnt lgkmcnt(7)
	v_mfma_f32_16x16x32_bf16 v[8:11], v[222:225], v[182:185], v[8:11]
	ds_read_b128 v[222:225], v251 offset:53392
	s_waitcnt lgkmcnt(7)
	v_mfma_f32_16x16x32_bf16 v[12:15], v[226:229], v[182:185], v[12:15]
	ds_read_b128 v[226:229], v251 offset:58000
	s_waitcnt lgkmcnt(7)
	v_mfma_f32_16x16x32_bf16 v[16:19], v[230:233], v[182:185], v[16:19]
	ds_read_b128 v[230:233], v251 offset:53312
	s_waitcnt lgkmcnt(7)
	v_mfma_f32_16x16x32_bf16 v[20:23], v[234:237], v[182:185], v[20:23]
	v_cvt_pk_bf16_f32 v88, v0, v1
	v_cvt_pk_bf16_f32 v89, v2, v3
	v_cvt_pk_bf16_f32 v90, v4, v5
	v_cvt_pk_bf16_f32 v91, v6, v7
	ds_read_b128 v[234:237], v251 offset:57920
	s_waitcnt lgkmcnt(7)
	v_mfma_f32_16x16x32_bf16 v[24:27], v[238:241], v[182:185], v[24:27]
	ds_read_b128 v[238:241], v251 offset:53456
	s_waitcnt lgkmcnt(7)
	v_mfma_f32_16x16x32_bf16 v[28:31], v[242:245], v[182:185], v[28:31]
	v_cvt_pk_bf16_f32 v84, v8, v9
	v_cvt_pk_bf16_f32 v85, v10, v11
	v_cvt_pk_bf16_f32 v86, v12, v13
	v_cvt_pk_bf16_f32 v87, v14, v15
	ds_read_b128 v[242:245], v251 offset:58064
	s_waitcnt lgkmcnt(7)
	v_mfma_f32_16x16x32_bf16 v[198:201], v[214:217], v[246:249], v[198:201]
	s_waitcnt lgkmcnt(6)
	v_mfma_f32_16x16x32_bf16 v[202:205], v[218:221], v[246:249], v[202:205]
	s_waitcnt lgkmcnt(5)
	v_mfma_f32_16x16x32_bf16 v[206:209], v[222:225], v[246:249], v[206:209]
	v_cvt_pk_bf16_f32 v80, v16, v17
	v_cvt_pk_bf16_f32 v81, v18, v19
	v_cvt_pk_bf16_f32 v82, v20, v21
	v_cvt_pk_bf16_f32 v83, v22, v23
	s_waitcnt lgkmcnt(4)
	v_mfma_f32_16x16x32_bf16 v[210:213], v[226:229], v[246:249], v[210:213]
	s_waitcnt lgkmcnt(3)
	v_mfma_f32_16x16x32_bf16 v[198:201], v[230:233], v[182:185], v[198:201]
	s_waitcnt lgkmcnt(2)
	v_mfma_f32_16x16x32_bf16 v[202:205], v[234:237], v[182:185], v[202:205]
	v_cvt_pk_bf16_f32 v76, v24, v25
	v_cvt_pk_bf16_f32 v77, v26, v27
	v_cvt_pk_bf16_f32 v78, v28, v29
	v_cvt_pk_bf16_f32 v79, v30, v31
	s_waitcnt lgkmcnt(1)
	v_mfma_f32_16x16x32_bf16 v[206:209], v[238:241], v[182:185], v[206:209]
	s_waitcnt lgkmcnt(0)
	v_mfma_f32_16x16x32_bf16 v[210:213], v[242:245], v[182:185], v[210:213]
	s_mov_b64 s[10:11], 0x1000
	v_lshl_add_u64 v[214:215], v[162:163], 0, s[10:11]
	s_mov_b64 s[10:11], 0x9000
	v_lshl_add_u64 v[216:217], v[162:163], 0, s[10:11]
	s_mov_b64 s[10:11], 0x11000
	v_lshl_add_u64 v[218:219], v[162:163], 0, s[10:11]
	s_mov_b64 s[10:11], 0x19000
	v_lshl_add_u64 v[220:221], v[162:163], 0, s[10:11]
	s_add_i32 s9, s9, 1
	global_store_dword v[214:215], v198, off offset:-4096
	global_store_dword v[214:215], v199, off offset:-2048
	global_store_dword v[214:215], v200, off
	global_store_dword v[214:215], v201, off offset:2048
	global_store_dword v[216:217], v202, off offset:-4096
	global_store_dword v[216:217], v203, off offset:-2048
	global_store_dword v[216:217], v204, off
	global_store_dword v[216:217], v205, off offset:2048
	global_store_dword v[218:219], v206, off offset:-4096
	global_store_dword v[218:219], v207, off offset:-2048
	global_store_dword v[218:219], v208, off
	global_store_dword v[218:219], v209, off offset:2048
	global_store_dword v[220:221], v210, off offset:-4096
	global_store_dword v[220:221], v211, off offset:-2048
	global_store_dword v[220:221], v212, off
	global_store_dword v[220:221], v213, off offset:2048
	s_cmp_eq_u32 s9, 32
	s_barrier
	s_cbranch_scc1 .LBB0_106
	s_waitcnt vmcnt(16)
	v_mov_b64_e32 v[102:103], v[34:35]
	v_mov_b64_e32 v[94:95], v[38:39]
	v_mov_b64_e32 v[98:99], v[42:43]
	v_mov_b64_e32 v[106:107], v[46:47]
	v_mov_b64_e32 v[100:101], v[32:33]
	v_mov_b64_e32 v[92:93], v[36:37]
	v_mov_b64_e32 v[96:97], v[40:41]
	v_mov_b64_e32 v[104:105], v[44:45]
	v_mov_b32_e32 v150, v128
	s_branch .LBB0_108
